# v43 + attention epilogue reduction xor-4/xor-8 via DPP row_half_mirror / row_ror:8 (quads already uniform, bit-identical)
# baseline (speedup 1.0000x reference)
; __device__ __forceinline__ int crow(int r, int hi) { return (r & 3) + 8 * (r >> 2) + 4 * hi; }
; __device__ __forceinline__ bool fox_block(const BlockRef& cur, BlockRef& nxt, unsigned* ctr, const unsigned* nrm, bf16_t* PROJ, bf16_t* MIX, char* lds, Seam& S, const float* __restrict__ CF, const float* __restrict__ fnorm) {
;     ...
;     for (int r = 0; r < 16; ++r) { const float rl = __builtin_amdgcn_rcpf(li_l[crow(r, hi)]); float a = 0.f;
; #pragma unroll
;         for (int d0 = 0; d0 < 4; ++d0) { const float v = o[d0][r] * rl; o[d0][r] = v; a += v * v; }
;         a += __shfl_xor(a, 1); a += __shfl_xor(a, 2); a += __shfl_xor(a, 4); a += __shfl_xor(a, 8); a += __shfl_xor(a, 16);
;         rs[r] = rsqrtf(a * (1.f / 128.f) + RMS_EPS); }
.LBB0_822:
	s_ashr_i32 s73, s72, 31
	s_waitcnt vmcnt(8)
	s_waitcnt vmcnt(0) lgkmcnt(0)
	ds_write_b128 v213, v[102:105] offset:32768
	ds_write_b128 v213, v[110:113] offset:40960
	v_cmp_gt_u32_e32 vcc, 32, v214
	s_and_saveexec_b64 s[10:11], vcc
	ds_write_b32 v215, v114
	s_or_b64 exec, exec, s[10:11]
	v_and_b32_e32 v67, 64, v207
	v_xor_b32_e32 v66, 1, v207
	v_add_u32_e32 v67, 64, v67
	v_cmp_lt_i32_e32 vcc, v66, v67
	s_waitcnt lgkmcnt(0)
	v_mov_b32_e32 v74, v50
	v_mov_b32_e32 v75, v34
	v_cndmask_b32_e32 v66, v207, v66, vcc
	v_lshlrev_b32_e32 v116, 2, v66
	v_xor_b32_e32 v66, 2, v207
	v_cmp_lt_i32_e32 vcc, v66, v67
	v_mov_b32_e32 v34, v51
	v_lshl_or_b32 v196, s22, 7, v211
	v_cndmask_b32_e32 v66, v207, v66, vcc
	v_lshlrev_b32_e32 v118, 2, v66
	v_xor_b32_e32 v66, 4, v207
	v_cmp_lt_i32_e32 vcc, v66, v67
	s_nop 1
	v_cndmask_b32_e32 v66, v207, v66, vcc
	v_lshlrev_b32_e32 v119, 2, v66
	v_xor_b32_e32 v66, 8, v207
	v_cmp_lt_i32_e32 vcc, v66, v67
	s_nop 1
	v_cndmask_b32_e32 v66, v207, v66, vcc
	v_lshlrev_b32_e32 v120, 2, v66
	v_xor_b32_e32 v66, 16, v207
	v_cmp_lt_i32_e32 vcc, v66, v67
	s_nop 1
	v_cndmask_b32_e32 v66, v207, v66, vcc
	v_lshlrev_b32_e32 v121, 2, v66
	ds_read_b128 v[70:73], v212
	ds_read_b128 v[66:69], v212 offset:32
	s_waitcnt lgkmcnt(0)
	v_rcp_f32_e32 v70, v70
	s_nop 0
	v_pk_mul_f32 v[86:87], v[74:75], v[70:71] op_sel_hi:[1,0]
	v_mov_b32_e32 v74, v2
	v_rcp_f32_e32 v2, v71
	v_mov_b32_e32 v75, v18
	v_mov_b32_e32 v18, v3
	v_pk_mul_f32 v[76:77], v[86:87], v[86:87]
	v_pk_mul_f32 v[80:81], v[34:35], v[2:3] op_sel_hi:[1,0]
	v_pk_mul_f32 v[84:85], v[74:75], v[70:71] op_sel_hi:[1,0]
	v_pk_mul_f32 v[34:35], v[80:81], v[80:81]
	v_pk_mul_f32 v[74:75], v[18:19], v[2:3] op_sel_hi:[1,0]
	v_pk_mul_f32 v[78:79], v[84:85], v[84:85]
	v_pk_mul_f32 v[2:3], v[74:75], v[74:75]
	v_mov_b32_e32 v18, v34
	v_mov_b32_e32 v19, v76
	v_mov_b32_e32 v76, v35
	v_pk_add_f32 v[18:19], v[18:19], v[76:77]
	v_mov_b32_e32 v34, v3
	v_mov_b32_e32 v35, v79
	v_pk_add_f32 v[18:19], v[34:35], v[18:19]
	v_mov_b32_e32 v3, v78
	v_pk_add_f32 v[2:3], v[2:3], v[18:19]
	s_nop 1
	v_mov_b32_dpp v19, v3 quad_perm:[1,0,3,2] row_mask:0xf bank_mask:0xf
	s_nop 1
	v_mov_b32_dpp v18, v2 quad_perm:[1,0,3,2] row_mask:0xf bank_mask:0xf
	v_mov_b32_e32 v34, v4
	v_rcp_f32_e32 v4, v73
	v_mov_b32_e32 v35, v20
	v_mov_b32_e32 v20, v5
	s_waitcnt lgkmcnt(0)
	v_pk_add_f32 v[2:3], v[2:3], v[18:19]
	s_nop 1
	v_mov_b32_dpp v19, v3 quad_perm:[2,3,0,1] row_mask:0xf bank_mask:0xf
	s_nop 1
	v_mov_b32_dpp v18, v2 quad_perm:[2,3,0,1] row_mask:0xf bank_mask:0xf
	s_waitcnt lgkmcnt(0)
	v_pk_add_f32 v[2:3], v[2:3], v[18:19]
	s_nop 1
	v_mov_b32_dpp v19, v3 row_half_mirror row_mask:0xf bank_mask:0xf
	s_nop 1
	v_mov_b32_dpp v18, v2 row_half_mirror row_mask:0xf bank_mask:0xf
	s_waitcnt lgkmcnt(0)
	v_pk_add_f32 v[2:3], v[2:3], v[18:19]
	s_nop 1
	v_mov_b32_dpp v19, v3 row_ror:8 row_mask:0xf bank_mask:0xf
	s_nop 1
	v_mov_b32_dpp v18, v2 row_ror:8 row_mask:0xf bank_mask:0xf
	s_waitcnt lgkmcnt(0)
	v_pk_add_f32 v[2:3], v[2:3], v[18:19]
	ds_bpermute_b32 v19, v121, v3
	ds_bpermute_b32 v18, v121, v2
	s_waitcnt lgkmcnt(0)
	v_pk_add_f32 v[2:3], v[2:3], v[18:19]
	s_nop 0
	v_pk_fma_f32 v[94:95], v[2:3], s[48:49], v[198:199] op_sel_hi:[1,0,0]
	v_mov_b32_e32 v18, v52
	v_mul_f32_e32 v2, 0x4b800000, v95
	v_cmp_gt_f32_e64 s[10:11], s44, v95
	v_mov_b32_e32 v19, v36
	v_mov_b32_e32 v36, v53
	v_cndmask_b32_e64 v2, v95, v2, s[10:11]
	v_rsq_f32_e32 v2, v2
	v_pk_mul_f32 v[78:79], v[36:37], v[4:5] op_sel_hi:[1,0]
	v_cmp_gt_f32_e32 vcc, s44, v94
	v_mul_f32_e32 v3, 0x45800000, v2
	v_cndmask_b32_e64 v117, v2, v3, s[10:11]
	v_rcp_f32_e32 v2, v72
	v_pk_mul_f32 v[72:73], v[20:21], v[4:5] op_sel_hi:[1,0]
	s_lshl_b64 s[10:11], s[72:73], 12
	v_pk_mul_f32 v[4:5], v[72:73], v[72:73]
	v_pk_mul_f32 v[88:89], v[18:19], v[2:3] op_sel_hi:[1,0]
	v_pk_mul_f32 v[82:83], v[34:35], v[2:3] op_sel_hi:[1,0]
	v_pk_mul_f32 v[18:19], v[88:89], v[88:89]
	v_pk_mul_f32 v[34:35], v[78:79], v[78:79]
	v_pk_mul_f32 v[2:3], v[82:83], v[82:83]
	v_mov_b32_e32 v20, v34
	v_mov_b32_e32 v21, v18
	v_mov_b32_e32 v18, v35
	v_pk_add_f32 v[18:19], v[20:21], v[18:19]
	v_mov_b32_e32 v20, v5
	v_mov_b32_e32 v21, v3
	v_pk_add_f32 v[18:19], v[20:21], v[18:19]
	v_mov_b32_e32 v5, v2
	v_pk_add_f32 v[2:3], v[4:5], v[18:19]
	s_nop 1
	v_mov_b32_dpp v5, v3 quad_perm:[1,0,3,2] row_mask:0xf bank_mask:0xf
	s_nop 1
	v_mov_b32_dpp v4, v2 quad_perm:[1,0,3,2] row_mask:0xf bank_mask:0xf
	v_mov_b32_e32 v18, v6
	v_rcp_f32_e32 v6, v67
	v_mov_b32_e32 v19, v22
	v_mov_b32_e32 v22, v7
	s_waitcnt lgkmcnt(0)
	v_pk_add_f32 v[2:3], v[2:3], v[4:5]
	s_nop 1
	v_mov_b32_dpp v5, v3 quad_perm:[2,3,0,1] row_mask:0xf bank_mask:0xf
	s_nop 1
	v_mov_b32_dpp v4, v2 quad_perm:[2,3,0,1] row_mask:0xf bank_mask:0xf
	v_pk_mul_f32 v[50:51], v[22:23], v[6:7] op_sel_hi:[1,0]
	s_add_u32 s12, s70, s10
	s_addc_u32 s13, s71, s11
	s_waitcnt lgkmcnt(0)
	v_pk_add_f32 v[2:3], v[2:3], v[4:5]
	s_nop 1
	v_mov_b32_dpp v5, v3 row_half_mirror row_mask:0xf bank_mask:0xf
	s_nop 1
	v_mov_b32_dpp v4, v2 row_half_mirror row_mask:0xf bank_mask:0xf
	s_waitcnt lgkmcnt(0)
	v_pk_add_f32 v[2:3], v[2:3], v[4:5]
	s_nop 1
	v_mov_b32_dpp v5, v3 row_ror:8 row_mask:0xf bank_mask:0xf
	s_nop 1
	v_mov_b32_dpp v4, v2 row_ror:8 row_mask:0xf bank_mask:0xf
	s_waitcnt lgkmcnt(0)
; __device__ __forceinline__ int crow(int r, int hi) { return (r & 3) + 8 * (r >> 2) + 4 * hi; }
; __device__ __forceinline__ bool fox_block(const BlockRef& cur, BlockRef& nxt, unsigned* ctr, const unsigned* nrm, bf16_t* PROJ, bf16_t* MIX, char* lds, Seam& S, const float* __restrict__ CF, const float* __restrict__ fnorm) {
;     ...
;     for (int r = 0; r < 16; ++r) { const float rl = __builtin_amdgcn_rcpf(li_l[crow(r, hi)]); float a = 0.f;
; #pragma unroll
;         for (int d0 = 0; d0 < 4; ++d0) { const float v = o[d0][r] * rl; o[d0][r] = v; a += v * v; }
;         a += __shfl_xor(a, 1); a += __shfl_xor(a, 2); a += __shfl_xor(a, 4); a += __shfl_xor(a, 8); a += __shfl_xor(a, 16);
;         rs[r] = rsqrtf(a * (1.f / 128.f) + RMS_EPS); }
	v_pk_add_f32 v[96:97], v[2:3], v[4:5]
	v_rcp_f32_e32 v2, v66
	v_mov_b32_e32 v4, v54
	v_mov_b32_e32 v5, v38
	v_mov_b32_e32 v38, v55
	v_pk_mul_f32 v[76:77], v[4:5], v[2:3] op_sel_hi:[1,0]
	v_pk_mul_f32 v[54:55], v[38:39], v[6:7] op_sel_hi:[1,0]
	v_pk_mul_f32 v[4:5], v[76:77], v[76:77]
	v_pk_mul_f32 v[70:71], v[18:19], v[2:3] op_sel_hi:[1,0]
	v_pk_mul_f32 v[18:19], v[54:55], v[54:55]
	v_pk_mul_f32 v[2:3], v[70:71], v[70:71]
	v_pk_mul_f32 v[6:7], v[50:51], v[50:51]
	v_mov_b32_e32 v20, v18
	v_mov_b32_e32 v21, v4
	v_mov_b32_e32 v4, v19
	v_pk_add_f32 v[4:5], v[20:21], v[4:5]
	v_mov_b32_e32 v18, v7
	v_mov_b32_e32 v19, v3
	v_pk_add_f32 v[4:5], v[18:19], v[4:5]
	v_mov_b32_e32 v7, v2
	v_pk_add_f32 v[2:3], v[6:7], v[4:5]
	s_nop 1
	v_mov_b32_dpp v5, v3 quad_perm:[1,0,3,2] row_mask:0xf bank_mask:0xf
	s_nop 1
	v_mov_b32_dpp v4, v2 quad_perm:[1,0,3,2] row_mask:0xf bank_mask:0xf
	v_mov_b32_e32 v6, v8
	v_mov_b32_e32 v7, v24
	v_mov_b32_e32 v24, v9
	ds_bpermute_b32 v115, v121, v97
	s_waitcnt lgkmcnt(0)
	v_pk_add_f32 v[2:3], v[2:3], v[4:5]
	s_nop 1
	v_mov_b32_dpp v5, v3 quad_perm:[2,3,0,1] row_mask:0xf bank_mask:0xf
	s_nop 1
	v_mov_b32_dpp v4, v2 quad_perm:[2,3,0,1] row_mask:0xf bank_mask:0xf
	ds_bpermute_b32 v114, v121, v96
	s_waitcnt lgkmcnt(0)
	v_pk_add_f32 v[2:3], v[2:3], v[4:5]
	s_nop 1
	v_mov_b32_dpp v5, v3 row_half_mirror row_mask:0xf bank_mask:0xf
	s_nop 1
	v_mov_b32_dpp v4, v2 row_half_mirror row_mask:0xf bank_mask:0xf
	s_waitcnt lgkmcnt(0)
	v_pk_add_f32 v[2:3], v[2:3], v[4:5]
	s_nop 1
	v_mov_b32_dpp v5, v3 row_ror:8 row_mask:0xf bank_mask:0xf
	s_nop 1
	v_mov_b32_dpp v4, v2 row_ror:8 row_mask:0xf bank_mask:0xf
	s_waitcnt lgkmcnt(0)
	v_pk_add_f32 v[90:91], v[2:3], v[4:5]
	v_rcp_f32_e32 v2, v68
	v_mov_b32_e32 v4, v56
	v_mov_b32_e32 v5, v40
	v_mov_b32_e32 v40, v57
	v_pk_mul_f32 v[52:53], v[6:7], v[2:3] op_sel_hi:[1,0]
	v_rcp_f32_e32 v6, v69
	v_pk_mul_f32 v[66:67], v[4:5], v[2:3] op_sel_hi:[1,0]
	v_pk_mul_f32 v[2:3], v[52:53], v[52:53]
	v_pk_mul_f32 v[4:5], v[66:67], v[66:67]
	v_pk_mul_f32 v[40:41], v[40:41], v[6:7] op_sel_hi:[1,0]
	v_pk_mul_f32 v[36:37], v[24:25], v[6:7] op_sel_hi:[1,0]
	v_pk_mul_f32 v[18:19], v[40:41], v[40:41]
	v_pk_mul_f32 v[6:7], v[36:37], v[36:37]
	v_mov_b32_e32 v8, v18
	v_mov_b32_e32 v9, v4
	v_mov_b32_e32 v4, v19
	v_pk_add_f32 v[4:5], v[8:9], v[4:5]
	v_mov_b32_e32 v8, v7
	v_mov_b32_e32 v9, v3
	v_pk_add_f32 v[4:5], v[8:9], v[4:5]
	v_mov_b32_e32 v7, v2
	v_pk_add_f32 v[2:3], v[6:7], v[4:5]
	s_nop 1
	v_mov_b32_dpp v5, v3 quad_perm:[1,0,3,2] row_mask:0xf bank_mask:0xf
	s_nop 1
	v_mov_b32_dpp v4, v2 quad_perm:[1,0,3,2] row_mask:0xf bank_mask:0xf
	v_mov_b32_e32 v6, v58
	v_mov_b32_e32 v7, v42
	v_mov_b32_e32 v8, v10
	v_mov_b32_e32 v9, v26
	s_waitcnt lgkmcnt(0)
	v_pk_add_f32 v[2:3], v[2:3], v[4:5]
	s_nop 1
	v_mov_b32_dpp v5, v3 quad_perm:[2,3,0,1] row_mask:0xf bank_mask:0xf
	s_nop 1
	v_mov_b32_dpp v4, v2 quad_perm:[2,3,0,1] row_mask:0xf bank_mask:0xf
	v_mov_b32_e32 v42, v59
	v_mov_b32_e32 v26, v11
	ds_bpermute_b32 v93, v121, v91
	ds_bpermute_b32 v92, v121, v90
	s_waitcnt lgkmcnt(0)
	v_pk_add_f32 v[2:3], v[2:3], v[4:5]
	s_nop 1
	v_mov_b32_dpp v5, v3 row_half_mirror row_mask:0xf bank_mask:0xf
	s_nop 1
	v_mov_b32_dpp v4, v2 row_half_mirror row_mask:0xf bank_mask:0xf
	s_waitcnt lgkmcnt(0)
	v_pk_add_f32 v[2:3], v[2:3], v[4:5]
	s_nop 1
	v_mov_b32_dpp v5, v3 row_ror:8 row_mask:0xf bank_mask:0xf
	s_nop 1
	v_mov_b32_dpp v4, v2 row_ror:8 row_mask:0xf bank_mask:0xf
	s_waitcnt lgkmcnt(0)
	v_pk_add_f32 v[56:57], v[2:3], v[4:5]
	ds_read_b128 v[2:5], v212 offset:64
	ds_bpermute_b32 v69, v121, v57
	ds_bpermute_b32 v68, v121, v56
	s_waitcnt lgkmcnt(0)
	v_rcp_f32_e32 v2, v2
	s_nop 0
	v_pk_mul_f32 v[38:39], v[6:7], v[2:3] op_sel_hi:[1,0]
	v_pk_mul_f32 v[34:35], v[8:9], v[2:3] op_sel_hi:[1,0]
	v_rcp_f32_e32 v2, v3
	v_pk_mul_f32 v[6:7], v[38:39], v[38:39]
	v_pk_mul_f32 v[8:9], v[34:35], v[34:35]
	v_mov_b32_e32 v11, v6
	v_pk_mul_f32 v[24:25], v[42:43], v[2:3] op_sel_hi:[1,0]
	v_pk_mul_f32 v[20:21], v[26:27], v[2:3] op_sel_hi:[1,0]
	v_pk_mul_f32 v[18:19], v[24:25], v[24:25]
	v_pk_mul_f32 v[2:3], v[20:21], v[20:21]
	v_mov_b32_e32 v10, v18
	v_mov_b32_e32 v6, v19
	v_pk_add_f32 v[6:7], v[10:11], v[6:7]
	v_mov_b32_e32 v10, v3
	v_mov_b32_e32 v11, v9
	v_pk_add_f32 v[6:7], v[10:11], v[6:7]
	v_mov_b32_e32 v3, v8
	v_pk_add_f32 v[2:3], v[2:3], v[6:7]
	s_nop 1
	v_mov_b32_dpp v7, v3 quad_perm:[1,0,3,2] row_mask:0xf bank_mask:0xf
	s_nop 1
	v_mov_b32_dpp v6, v2 quad_perm:[1,0,3,2] row_mask:0xf bank_mask:0xf
	s_waitcnt lgkmcnt(0)
	v_pk_add_f32 v[2:3], v[2:3], v[6:7]
	s_nop 1
	v_mov_b32_dpp v7, v3 quad_perm:[2,3,0,1] row_mask:0xf bank_mask:0xf
	s_nop 1
	v_mov_b32_dpp v6, v2 quad_perm:[2,3,0,1] row_mask:0xf bank_mask:0xf
	s_waitcnt lgkmcnt(0)
	v_pk_add_f32 v[2:3], v[2:3], v[6:7]
	s_nop 1
	v_mov_b32_dpp v7, v3 row_half_mirror row_mask:0xf bank_mask:0xf
	s_nop 1
	v_mov_b32_dpp v6, v2 row_half_mirror row_mask:0xf bank_mask:0xf
	s_waitcnt lgkmcnt(0)
	v_pk_add_f32 v[2:3], v[2:3], v[6:7]
	s_nop 1
	v_mov_b32_dpp v7, v3 row_ror:8 row_mask:0xf bank_mask:0xf
	s_nop 1
	v_mov_b32_dpp v6, v2 row_ror:8 row_mask:0xf bank_mask:0xf
	s_waitcnt lgkmcnt(0)
; __device__ __forceinline__ unsigned cvt_pk_bf16(float lo, float hi) { unsigned r; asm volatile("v_cvt_pk_bf16_f32 %0, %1, %2" : "=v"(r) : "v"(lo), "v"(hi)); return r; }
; __device__ __forceinline__ int crow(int r, int hi) { return (r & 3) + 8 * (r >> 2) + 4 * hi; }
; __device__ __forceinline__ bool fox_block(const BlockRef& cur, BlockRef& nxt, unsigned* ctr, const unsigned* nrm, bf16_t* PROJ, bf16_t* MIX, char* lds, Seam& S, const float* __restrict__ CF, const float* __restrict__ fnorm) {
;     ...
;     for (int r = 0; r < 16; ++r) { const float rl = __builtin_amdgcn_rcpf(li_l[crow(r, hi)]); float a = 0.f;
; #pragma unroll
;         for (int d0 = 0; d0 < 4; ++d0) { const float v = o[d0][r] * rl; o[d0][r] = v; a += v * v; }
;         a += __shfl_xor(a, 1); a += __shfl_xor(a, 2); a += __shfl_xor(a, 4); a += __shfl_xor(a, 8); a += __shfl_xor(a, 16);
;         rs[r] = rsqrtf(a * (1.f / 128.f) + RMS_EPS); }
;     float gn[4];
; #pragma unroll
;     for (int d0 = 0; d0 < 4; ++d0) gn[d0] = fnorm[cur.head * 128 + d0 * 32 + r32];
;     bf16_t* Ow = cur.O + (size_t)(wid * QBLK) * DM;
; #pragma unroll
;     for (int r = 0; r < 16; ++r) { const int orow = crow(r, hi);
; #pragma unroll
;         for (int d0 = 0; d0 < 4; ++d0) { const float v = o[d0][r] * rs[r] * gn[d0];
;             const float vn = __shfl_xor(v, 1);
;             if ((r32 & 1) == 0) *(unsigned*)(Ow + (size_t)orow * DM + d0 * 32 + r32) = cvt_pk_bf16(v, vn); } }
	v_pk_add_f32 v[26:27], v[2:3], v[6:7]
	v_rcp_f32_e32 v2, v4
	v_rcp_f32_e32 v4, v5
	v_mov_b32_e32 v6, v60
	v_mov_b32_e32 v7, v44
	v_mov_b32_e32 v44, v61
	v_pk_mul_f32 v[18:19], v[6:7], v[2:3] op_sel_hi:[1,0]
	v_mov_b32_e32 v6, v12
	v_mov_b32_e32 v7, v28
	v_pk_mul_f32 v[8:9], v[44:45], v[4:5] op_sel_hi:[1,0]
	v_mov_b32_e32 v28, v13
	v_pk_mul_f32 v[22:23], v[18:19], v[18:19]
	v_pk_mul_f32 v[10:11], v[6:7], v[2:3] op_sel_hi:[1,0]
	v_pk_mul_f32 v[44:45], v[8:9], v[8:9]
	v_pk_mul_f32 v[6:7], v[28:29], v[4:5] op_sel_hi:[1,0]
	v_pk_mul_f32 v[2:3], v[10:11], v[10:11]
	v_pk_mul_f32 v[4:5], v[6:7], v[6:7]
	v_mov_b32_e32 v12, v44
	v_mov_b32_e32 v13, v22
	v_mov_b32_e32 v22, v45
	v_pk_add_f32 v[12:13], v[12:13], v[22:23]
	v_mov_b32_e32 v22, v5
	v_mov_b32_e32 v23, v3
	v_pk_add_f32 v[12:13], v[22:23], v[12:13]
	v_mov_b32_e32 v5, v2
	v_pk_add_f32 v[2:3], v[4:5], v[12:13]
	s_nop 1
	v_mov_b32_dpp v5, v3 quad_perm:[1,0,3,2] row_mask:0xf bank_mask:0xf
	s_nop 1
	v_mov_b32_dpp v4, v2 quad_perm:[1,0,3,2] row_mask:0xf bank_mask:0xf
	v_mov_b32_e32 v28, v62
	v_mov_b32_e32 v29, v46
	v_mov_b32_e32 v44, v14
	v_mov_b32_e32 v45, v30
	s_waitcnt lgkmcnt(0)
	v_pk_add_f32 v[2:3], v[2:3], v[4:5]
	s_nop 1
	v_mov_b32_dpp v5, v3 quad_perm:[2,3,0,1] row_mask:0xf bank_mask:0xf
	s_nop 1
	v_mov_b32_dpp v4, v2 quad_perm:[2,3,0,1] row_mask:0xf bank_mask:0xf
	v_mov_b32_e32 v46, v63
	v_mov_b32_e32 v30, v15
	ds_bpermute_b32 v43, v121, v27
	ds_bpermute_b32 v42, v121, v26
	s_waitcnt lgkmcnt(0)
	v_pk_add_f32 v[2:3], v[2:3], v[4:5]
	s_nop 1
	v_mov_b32_dpp v5, v3 row_half_mirror row_mask:0xf bank_mask:0xf
	s_nop 1
	v_mov_b32_dpp v4, v2 row_half_mirror row_mask:0xf bank_mask:0xf
	s_waitcnt lgkmcnt(0)
	v_pk_add_f32 v[2:3], v[2:3], v[4:5]
	s_nop 1
	v_mov_b32_dpp v5, v3 row_ror:8 row_mask:0xf bank_mask:0xf
	s_nop 1
	v_mov_b32_dpp v4, v2 row_ror:8 row_mask:0xf bank_mask:0xf
	s_waitcnt lgkmcnt(0)
	v_pk_add_f32 v[12:13], v[2:3], v[4:5]
	ds_read_b128 v[2:5], v212 offset:96
	ds_bpermute_b32 v23, v121, v13
	ds_bpermute_b32 v22, v121, v12
	s_waitcnt lgkmcnt(0)
	v_rcp_f32_e32 v2, v2
	s_nop 0
	v_pk_mul_f32 v[60:61], v[28:29], v[2:3] op_sel_hi:[1,0]
	v_pk_mul_f32 v[58:59], v[44:45], v[2:3] op_sel_hi:[1,0]
	v_rcp_f32_e32 v2, v3
	v_pk_mul_f32 v[28:29], v[60:61], v[60:61]
	v_pk_mul_f32 v[122:123], v[58:59], v[58:59]
	v_mov_b32_e32 v15, v28
	v_pk_mul_f32 v[44:45], v[46:47], v[2:3] op_sel_hi:[1,0]
	v_pk_mul_f32 v[30:31], v[30:31], v[2:3] op_sel_hi:[1,0]
	v_pk_mul_f32 v[46:47], v[44:45], v[44:45]
	v_pk_mul_f32 v[2:3], v[30:31], v[30:31]
	v_mov_b32_e32 v14, v46
	v_mov_b32_e32 v28, v47
	v_pk_add_f32 v[14:15], v[14:15], v[28:29]
	v_mov_b32_e32 v28, v3
	v_mov_b32_e32 v29, v123
	v_pk_add_f32 v[14:15], v[28:29], v[14:15]
	v_mov_b32_e32 v3, v122
	v_pk_add_f32 v[2:3], v[2:3], v[14:15]
	s_nop 1
	v_mov_b32_dpp v15, v3 quad_perm:[1,0,3,2] row_mask:0xf bank_mask:0xf
	s_nop 1
	v_mov_b32_dpp v14, v2 quad_perm:[1,0,3,2] row_mask:0xf bank_mask:0xf
	s_waitcnt lgkmcnt(0)
	v_pk_add_f32 v[2:3], v[2:3], v[14:15]
	s_nop 1
	v_mov_b32_dpp v15, v3 quad_perm:[2,3,0,1] row_mask:0xf bank_mask:0xf
	s_nop 1
	v_mov_b32_dpp v14, v2 quad_perm:[2,3,0,1] row_mask:0xf bank_mask:0xf
	s_waitcnt lgkmcnt(0)
	v_pk_add_f32 v[2:3], v[2:3], v[14:15]
	s_nop 1
	v_mov_b32_dpp v15, v3 row_half_mirror row_mask:0xf bank_mask:0xf
	s_nop 1
	v_mov_b32_dpp v14, v2 row_half_mirror row_mask:0xf bank_mask:0xf
	s_waitcnt lgkmcnt(0)
	v_pk_add_f32 v[2:3], v[2:3], v[14:15]
	s_nop 1
	v_mov_b32_dpp v15, v3 row_ror:8 row_mask:0xf bank_mask:0xf
	s_nop 1
	v_mov_b32_dpp v14, v2 row_ror:8 row_mask:0xf bank_mask:0xf
	s_waitcnt lgkmcnt(0)
	v_pk_add_f32 v[46:47], v[2:3], v[14:15]
	v_rcp_f32_e32 v2, v4
	v_mov_b32_e32 v14, v64
	v_mov_b32_e32 v15, v48
	v_mov_b32_e32 v48, v65
	v_pk_mul_f32 v[28:29], v[14:15], v[2:3] op_sel_hi:[1,0]
	v_mov_b32_e32 v14, v16
	v_mov_b32_e32 v15, v32
	v_pk_mul_f32 v[14:15], v[14:15], v[2:3] op_sel_hi:[1,0]
	v_rcp_f32_e32 v2, v5
	v_mov_b32_e32 v32, v17
	v_pk_mul_f32 v[122:123], v[28:29], v[28:29]
	v_pk_mul_f32 v[124:125], v[14:15], v[14:15]
	v_pk_mul_f32 v[4:5], v[48:49], v[2:3] op_sel_hi:[1,0]
	v_pk_mul_f32 v[2:3], v[32:33], v[2:3] op_sel_hi:[1,0]
	v_pk_mul_f32 v[48:49], v[4:5], v[4:5]
	v_pk_mul_f32 v[16:17], v[2:3], v[2:3]
	v_mov_b32_e32 v32, v48
	v_mov_b32_e32 v33, v122
	v_mov_b32_e32 v122, v49
	v_pk_add_f32 v[32:33], v[32:33], v[122:123]
	v_mov_b32_e32 v48, v17
	v_mov_b32_e32 v49, v125
	v_pk_add_f32 v[32:33], v[48:49], v[32:33]
	v_mov_b32_e32 v17, v124
	v_pk_add_f32 v[16:17], v[16:17], v[32:33]
	s_nop 1
	v_mov_b32_dpp v33, v17 quad_perm:[1,0,3,2] row_mask:0xf bank_mask:0xf
	s_nop 1
	v_mov_b32_dpp v32, v16 quad_perm:[1,0,3,2] row_mask:0xf bank_mask:0xf
	v_lshl_add_u64 v[48:49], v[196:197], 2, s[18:19]
	v_mul_f32_e32 v64, v86, v117
	ds_bpermute_b32 v63, v121, v47
	ds_bpermute_b32 v62, v121, v46
	s_waitcnt lgkmcnt(0)
	v_pk_add_f32 v[16:17], v[16:17], v[32:33]
	s_nop 1
	v_mov_b32_dpp v33, v17 quad_perm:[2,3,0,1] row_mask:0xf bank_mask:0xf
	s_nop 1
	v_mov_b32_dpp v32, v16 quad_perm:[2,3,0,1] row_mask:0xf bank_mask:0xf
	v_lshlrev_b32_e32 v196, 1, v211
	s_waitcnt lgkmcnt(0)
	v_pk_add_f32 v[16:17], v[16:17], v[32:33]
	s_nop 1
	v_mov_b32_dpp v33, v17 row_half_mirror row_mask:0xf bank_mask:0xf
	s_nop 1
	v_mov_b32_dpp v32, v16 row_half_mirror row_mask:0xf bank_mask:0xf
	s_waitcnt lgkmcnt(0)
	v_pk_add_f32 v[16:17], v[16:17], v[32:33]
	s_nop 1
	v_mov_b32_dpp v33, v17 row_ror:8 row_mask:0xf bank_mask:0xf
	s_nop 1
	v_mov_b32_dpp v32, v16 row_ror:8 row_mask:0xf bank_mask:0xf
	flat_load_dword v120, v[48:49]
	flat_load_dword v119, v[48:49] offset:128
	flat_load_dword v118, v[48:49] offset:256
	flat_load_dword v95, v[48:49] offset:384
	v_and_b32_e32 v48, 1, v202
	v_cmp_eq_u32_e64 s[10:11], 0, v48
	v_lshl_add_u64 v[48:49], s[12:13], 0, v[196:197]
	s_waitcnt lgkmcnt(0)
	v_pk_add_f32 v[16:17], v[16:17], v[32:33]
	ds_bpermute_b32 v33, v121, v17
	ds_bpermute_b32 v32, v121, v16
	v_lshlrev_b32_e32 v196, 14, v203
	v_lshl_add_u64 v[48:49], v[48:49], 0, v[196:197]
	s_waitcnt vmcnt(0)
	v_mul_f32_e32 v64, v64, v120
	s_nop 1
	v_mov_b32_dpp v65, v64 quad_perm:[1,0,3,2] row_mask:0xf bank_mask:0xf
	s_and_saveexec_b64 s[12:13], s[10:11]
	s_cbranch_execz .LBB0_826
	s_waitcnt lgkmcnt(0)
	v_cvt_pk_bf16_f32 v64, v64, v65
	global_store_dword v[48:49], v64, off

; __device__ __forceinline__ int crow(int r, int hi) { return (r & 3) + 8 * (r >> 2) + 4 * hi; }
; __device__ __forceinline__ bool fox_block(const BlockRef& cur, BlockRef& nxt, unsigned* ctr, const unsigned* nrm, bf16_t* PROJ, bf16_t* MIX, char* lds, Seam& S, const float* __restrict__ CF, const float* __restrict__ fnorm) {
;     ...
;     if (hi == 0) li_l[r32] = l_reg; asm volatile("s_waitcnt lgkmcnt(0)" ::: "memory");
;     float rs[16];
; #pragma unroll
;     for (int r = 0; r < 16; ++r) { const float rl = __builtin_amdgcn_rcpf(li_l[crow(r, hi)]); float a = 0.f;
; #pragma unroll
;         for (int d0 = 0; d0 < 4; ++d0) { const float v = o[d0][r] * rl; o[d0][r] = v; a += v * v; }
;         a += __shfl_xor(a, 1); a += __shfl_xor(a, 2); a += __shfl_xor(a, 4); a += __shfl_xor(a, 8); a += __shfl_xor(a, 16);
;         rs[r] = rsqrtf(a * (1.f / 128.f) + RMS_EPS); }
.LBB0_2250:
	s_ashr_i32 s73, s72, 31
	s_waitcnt vmcnt(8)
	s_waitcnt vmcnt(0) lgkmcnt(0)
	ds_write_b128 v213, v[102:105] offset:32768
	ds_write_b128 v213, v[110:113] offset:40960
	v_cmp_gt_u32_e32 vcc, 32, v214
	s_and_saveexec_b64 s[10:11], vcc
	ds_write_b32 v215, v114
	s_or_b64 exec, exec, s[10:11]
	v_and_b32_e32 v67, 64, v207
	v_xor_b32_e32 v66, 1, v207
	v_add_u32_e32 v67, 64, v67
	v_cmp_lt_i32_e32 vcc, v66, v67
	s_waitcnt lgkmcnt(0)
	v_mov_b32_e32 v74, v50
	v_mov_b32_e32 v75, v34
	v_cndmask_b32_e32 v66, v207, v66, vcc
	v_lshlrev_b32_e32 v116, 2, v66
	v_xor_b32_e32 v66, 2, v207
	v_cmp_lt_i32_e32 vcc, v66, v67
	v_mov_b32_e32 v34, v51
	v_lshl_or_b32 v196, s22, 7, v211
	v_cndmask_b32_e32 v66, v207, v66, vcc
	v_lshlrev_b32_e32 v118, 2, v66
	v_xor_b32_e32 v66, 4, v207
	v_cmp_lt_i32_e32 vcc, v66, v67
	s_nop 1
	v_cndmask_b32_e32 v66, v207, v66, vcc
	v_lshlrev_b32_e32 v119, 2, v66
	v_xor_b32_e32 v66, 8, v207
	v_cmp_lt_i32_e32 vcc, v66, v67
	s_nop 1
	v_cndmask_b32_e32 v66, v207, v66, vcc
	v_lshlrev_b32_e32 v120, 2, v66
	v_xor_b32_e32 v66, 16, v207
	v_cmp_lt_i32_e32 vcc, v66, v67
	s_nop 1
	v_cndmask_b32_e32 v66, v207, v66, vcc
	v_lshlrev_b32_e32 v121, 2, v66
	ds_read_b128 v[70:73], v212
	ds_read_b128 v[66:69], v212 offset:32
	s_waitcnt lgkmcnt(0)
	v_rcp_f32_e32 v70, v70
	s_nop 0
	v_pk_mul_f32 v[86:87], v[74:75], v[70:71] op_sel_hi:[1,0]
	v_mov_b32_e32 v74, v2
	v_rcp_f32_e32 v2, v71
	v_mov_b32_e32 v75, v18
	v_mov_b32_e32 v18, v3
	v_pk_mul_f32 v[76:77], v[86:87], v[86:87]
	v_pk_mul_f32 v[80:81], v[34:35], v[2:3] op_sel_hi:[1,0]
	v_pk_mul_f32 v[84:85], v[74:75], v[70:71] op_sel_hi:[1,0]
	v_pk_mul_f32 v[34:35], v[80:81], v[80:81]
	v_pk_mul_f32 v[74:75], v[18:19], v[2:3] op_sel_hi:[1,0]
	v_pk_mul_f32 v[78:79], v[84:85], v[84:85]
	v_pk_mul_f32 v[2:3], v[74:75], v[74:75]
	v_mov_b32_e32 v18, v34
	v_mov_b32_e32 v19, v76
	v_mov_b32_e32 v76, v35
	v_pk_add_f32 v[18:19], v[18:19], v[76:77]
	v_mov_b32_e32 v34, v3
	v_mov_b32_e32 v35, v79
	v_pk_add_f32 v[18:19], v[34:35], v[18:19]
	v_mov_b32_e32 v3, v78
	v_pk_add_f32 v[2:3], v[2:3], v[18:19]
	s_nop 1
	v_mov_b32_dpp v19, v3 quad_perm:[1,0,3,2] row_mask:0xf bank_mask:0xf
	s_nop 1
	v_mov_b32_dpp v18, v2 quad_perm:[1,0,3,2] row_mask:0xf bank_mask:0xf
	v_mov_b32_e32 v34, v4
	v_rcp_f32_e32 v4, v73
	v_mov_b32_e32 v35, v20
	v_mov_b32_e32 v20, v5
	s_waitcnt lgkmcnt(0)
	v_pk_add_f32 v[2:3], v[2:3], v[18:19]
	s_nop 1
	v_mov_b32_dpp v19, v3 quad_perm:[2,3,0,1] row_mask:0xf bank_mask:0xf
	s_nop 1
	v_mov_b32_dpp v18, v2 quad_perm:[2,3,0,1] row_mask:0xf bank_mask:0xf
	s_waitcnt lgkmcnt(0)
	v_pk_add_f32 v[2:3], v[2:3], v[18:19]
	s_nop 1
	v_mov_b32_dpp v19, v3 row_half_mirror row_mask:0xf bank_mask:0xf
	s_nop 1
	v_mov_b32_dpp v18, v2 row_half_mirror row_mask:0xf bank_mask:0xf
	s_waitcnt lgkmcnt(0)
	v_pk_add_f32 v[2:3], v[2:3], v[18:19]
	s_nop 1
	v_mov_b32_dpp v19, v3 row_ror:8 row_mask:0xf bank_mask:0xf
	s_nop 1
	v_mov_b32_dpp v18, v2 row_ror:8 row_mask:0xf bank_mask:0xf
	s_waitcnt lgkmcnt(0)
	v_pk_add_f32 v[2:3], v[2:3], v[18:19]
	ds_bpermute_b32 v19, v121, v3
	ds_bpermute_b32 v18, v121, v2
	s_waitcnt lgkmcnt(0)
	v_pk_add_f32 v[2:3], v[2:3], v[18:19]
	s_nop 0
	v_pk_fma_f32 v[94:95], v[2:3], s[48:49], v[198:199] op_sel_hi:[1,0,0]
	v_mov_b32_e32 v18, v52
	v_mul_f32_e32 v2, 0x4b800000, v95
	v_cmp_gt_f32_e64 s[10:11], s44, v95
	v_mov_b32_e32 v19, v36
	v_mov_b32_e32 v36, v53
	v_cndmask_b32_e64 v2, v95, v2, s[10:11]
	v_rsq_f32_e32 v2, v2
	v_pk_mul_f32 v[78:79], v[36:37], v[4:5] op_sel_hi:[1,0]
	v_cmp_gt_f32_e32 vcc, s44, v94
	v_mul_f32_e32 v3, 0x45800000, v2
	v_cndmask_b32_e64 v117, v2, v3, s[10:11]
	v_rcp_f32_e32 v2, v72
	v_pk_mul_f32 v[72:73], v[20:21], v[4:5] op_sel_hi:[1,0]
	s_lshl_b64 s[10:11], s[72:73], 12
	v_pk_mul_f32 v[4:5], v[72:73], v[72:73]
	v_pk_mul_f32 v[88:89], v[18:19], v[2:3] op_sel_hi:[1,0]
	v_pk_mul_f32 v[82:83], v[34:35], v[2:3] op_sel_hi:[1,0]
	v_pk_mul_f32 v[18:19], v[88:89], v[88:89]
	v_pk_mul_f32 v[34:35], v[78:79], v[78:79]
	v_pk_mul_f32 v[2:3], v[82:83], v[82:83]
	v_mov_b32_e32 v20, v34
	v_mov_b32_e32 v21, v18
	v_mov_b32_e32 v18, v35
	v_pk_add_f32 v[18:19], v[20:21], v[18:19]
	v_mov_b32_e32 v20, v5
	v_mov_b32_e32 v21, v3
	v_pk_add_f32 v[18:19], v[20:21], v[18:19]
	v_mov_b32_e32 v5, v2
	v_pk_add_f32 v[2:3], v[4:5], v[18:19]
	s_nop 1
	v_mov_b32_dpp v5, v3 quad_perm:[1,0,3,2] row_mask:0xf bank_mask:0xf
	s_nop 1
	v_mov_b32_dpp v4, v2 quad_perm:[1,0,3,2] row_mask:0xf bank_mask:0xf
	v_mov_b32_e32 v18, v6
	v_rcp_f32_e32 v6, v67
	v_mov_b32_e32 v19, v22
	v_mov_b32_e32 v22, v7
	s_waitcnt lgkmcnt(0)
	v_pk_add_f32 v[2:3], v[2:3], v[4:5]
	s_nop 1
	v_mov_b32_dpp v5, v3 quad_perm:[2,3,0,1] row_mask:0xf bank_mask:0xf
	s_nop 1
	v_mov_b32_dpp v4, v2 quad_perm:[2,3,0,1] row_mask:0xf bank_mask:0xf
	v_pk_mul_f32 v[50:51], v[22:23], v[6:7] op_sel_hi:[1,0]
	s_add_u32 s12, s70, s10
	s_addc_u32 s13, s71, s11
	s_waitcnt lgkmcnt(0)
	v_pk_add_f32 v[2:3], v[2:3], v[4:5]
	s_nop 1
	v_mov_b32_dpp v5, v3 row_half_mirror row_mask:0xf bank_mask:0xf
	s_nop 1
	v_mov_b32_dpp v4, v2 row_half_mirror row_mask:0xf bank_mask:0xf
	s_waitcnt lgkmcnt(0)
	v_pk_add_f32 v[2:3], v[2:3], v[4:5]
	s_nop 1
	v_mov_b32_dpp v5, v3 row_ror:8 row_mask:0xf bank_mask:0xf
	s_nop 1
	v_mov_b32_dpp v4, v2 row_ror:8 row_mask:0xf bank_mask:0xf
	s_waitcnt lgkmcnt(0)
; __device__ __forceinline__ int crow(int r, int hi) { return (r & 3) + 8 * (r >> 2) + 4 * hi; }
; __device__ __forceinline__ bool fox_block(const BlockRef& cur, BlockRef& nxt, unsigned* ctr, const unsigned* nrm, bf16_t* PROJ, bf16_t* MIX, char* lds, Seam& S, const float* __restrict__ CF, const float* __restrict__ fnorm) {
;     ...
;     for (int r = 0; r < 16; ++r) { const float rl = __builtin_amdgcn_rcpf(li_l[crow(r, hi)]); float a = 0.f;
; #pragma unroll
;         for (int d0 = 0; d0 < 4; ++d0) { const float v = o[d0][r] * rl; o[d0][r] = v; a += v * v; }
;         a += __shfl_xor(a, 1); a += __shfl_xor(a, 2); a += __shfl_xor(a, 4); a += __shfl_xor(a, 8); a += __shfl_xor(a, 16);
;         rs[r] = rsqrtf(a * (1.f / 128.f) + RMS_EPS); }
	v_pk_add_f32 v[96:97], v[2:3], v[4:5]
	v_rcp_f32_e32 v2, v66
	v_mov_b32_e32 v4, v54
	v_mov_b32_e32 v5, v38
	v_mov_b32_e32 v38, v55
	v_pk_mul_f32 v[76:77], v[4:5], v[2:3] op_sel_hi:[1,0]
	v_pk_mul_f32 v[54:55], v[38:39], v[6:7] op_sel_hi:[1,0]
	v_pk_mul_f32 v[4:5], v[76:77], v[76:77]
	v_pk_mul_f32 v[70:71], v[18:19], v[2:3] op_sel_hi:[1,0]
	v_pk_mul_f32 v[18:19], v[54:55], v[54:55]
	v_pk_mul_f32 v[2:3], v[70:71], v[70:71]
	v_pk_mul_f32 v[6:7], v[50:51], v[50:51]
	v_mov_b32_e32 v20, v18
	v_mov_b32_e32 v21, v4
	v_mov_b32_e32 v4, v19
	v_pk_add_f32 v[4:5], v[20:21], v[4:5]
	v_mov_b32_e32 v18, v7
	v_mov_b32_e32 v19, v3
	v_pk_add_f32 v[4:5], v[18:19], v[4:5]
	v_mov_b32_e32 v7, v2
	v_pk_add_f32 v[2:3], v[6:7], v[4:5]
	s_nop 1
	v_mov_b32_dpp v5, v3 quad_perm:[1,0,3,2] row_mask:0xf bank_mask:0xf
	s_nop 1
	v_mov_b32_dpp v4, v2 quad_perm:[1,0,3,2] row_mask:0xf bank_mask:0xf
	v_mov_b32_e32 v6, v8
	v_mov_b32_e32 v7, v24
	v_mov_b32_e32 v24, v9
	ds_bpermute_b32 v115, v121, v97
	s_waitcnt lgkmcnt(0)
	v_pk_add_f32 v[2:3], v[2:3], v[4:5]
	s_nop 1
	v_mov_b32_dpp v5, v3 quad_perm:[2,3,0,1] row_mask:0xf bank_mask:0xf
	s_nop 1
	v_mov_b32_dpp v4, v2 quad_perm:[2,3,0,1] row_mask:0xf bank_mask:0xf
	ds_bpermute_b32 v114, v121, v96
	s_waitcnt lgkmcnt(0)
	v_pk_add_f32 v[2:3], v[2:3], v[4:5]
	s_nop 1
	v_mov_b32_dpp v5, v3 row_half_mirror row_mask:0xf bank_mask:0xf
	s_nop 1
	v_mov_b32_dpp v4, v2 row_half_mirror row_mask:0xf bank_mask:0xf
	s_waitcnt lgkmcnt(0)
	v_pk_add_f32 v[2:3], v[2:3], v[4:5]
	s_nop 1
	v_mov_b32_dpp v5, v3 row_ror:8 row_mask:0xf bank_mask:0xf
	s_nop 1
	v_mov_b32_dpp v4, v2 row_ror:8 row_mask:0xf bank_mask:0xf
	s_waitcnt lgkmcnt(0)
	v_pk_add_f32 v[90:91], v[2:3], v[4:5]
	v_rcp_f32_e32 v2, v68
	v_mov_b32_e32 v4, v56
	v_mov_b32_e32 v5, v40
	v_mov_b32_e32 v40, v57
	v_pk_mul_f32 v[52:53], v[6:7], v[2:3] op_sel_hi:[1,0]
	v_rcp_f32_e32 v6, v69
	v_pk_mul_f32 v[66:67], v[4:5], v[2:3] op_sel_hi:[1,0]
	v_pk_mul_f32 v[2:3], v[52:53], v[52:53]
	v_pk_mul_f32 v[4:5], v[66:67], v[66:67]
	v_pk_mul_f32 v[40:41], v[40:41], v[6:7] op_sel_hi:[1,0]
	v_pk_mul_f32 v[36:37], v[24:25], v[6:7] op_sel_hi:[1,0]
	v_pk_mul_f32 v[18:19], v[40:41], v[40:41]
	v_pk_mul_f32 v[6:7], v[36:37], v[36:37]
	v_mov_b32_e32 v8, v18
	v_mov_b32_e32 v9, v4
	v_mov_b32_e32 v4, v19
	v_pk_add_f32 v[4:5], v[8:9], v[4:5]
	v_mov_b32_e32 v8, v7
	v_mov_b32_e32 v9, v3
	v_pk_add_f32 v[4:5], v[8:9], v[4:5]
	v_mov_b32_e32 v7, v2
	v_pk_add_f32 v[2:3], v[6:7], v[4:5]
	s_nop 1
	v_mov_b32_dpp v5, v3 quad_perm:[1,0,3,2] row_mask:0xf bank_mask:0xf
	s_nop 1
	v_mov_b32_dpp v4, v2 quad_perm:[1,0,3,2] row_mask:0xf bank_mask:0xf
	v_mov_b32_e32 v6, v58
	v_mov_b32_e32 v7, v42
	v_mov_b32_e32 v8, v10
	v_mov_b32_e32 v9, v26
	s_waitcnt lgkmcnt(0)
	v_pk_add_f32 v[2:3], v[2:3], v[4:5]
	s_nop 1
	v_mov_b32_dpp v5, v3 quad_perm:[2,3,0,1] row_mask:0xf bank_mask:0xf
	s_nop 1
	v_mov_b32_dpp v4, v2 quad_perm:[2,3,0,1] row_mask:0xf bank_mask:0xf
	v_mov_b32_e32 v42, v59
	v_mov_b32_e32 v26, v11
	ds_bpermute_b32 v93, v121, v91
	ds_bpermute_b32 v92, v121, v90
	s_waitcnt lgkmcnt(0)
	v_pk_add_f32 v[2:3], v[2:3], v[4:5]
	s_nop 1
	v_mov_b32_dpp v5, v3 row_half_mirror row_mask:0xf bank_mask:0xf
	s_nop 1
	v_mov_b32_dpp v4, v2 row_half_mirror row_mask:0xf bank_mask:0xf
	s_waitcnt lgkmcnt(0)
	v_pk_add_f32 v[2:3], v[2:3], v[4:5]
	s_nop 1
	v_mov_b32_dpp v5, v3 row_ror:8 row_mask:0xf bank_mask:0xf
	s_nop 1
	v_mov_b32_dpp v4, v2 row_ror:8 row_mask:0xf bank_mask:0xf
	s_waitcnt lgkmcnt(0)
	v_pk_add_f32 v[56:57], v[2:3], v[4:5]
	ds_read_b128 v[2:5], v212 offset:64
	ds_bpermute_b32 v69, v121, v57
	ds_bpermute_b32 v68, v121, v56
	s_waitcnt lgkmcnt(0)
	v_rcp_f32_e32 v2, v2
	s_nop 0
	v_pk_mul_f32 v[38:39], v[6:7], v[2:3] op_sel_hi:[1,0]
	v_pk_mul_f32 v[34:35], v[8:9], v[2:3] op_sel_hi:[1,0]
	v_rcp_f32_e32 v2, v3
	v_pk_mul_f32 v[6:7], v[38:39], v[38:39]
	v_pk_mul_f32 v[8:9], v[34:35], v[34:35]
	v_mov_b32_e32 v11, v6
	v_pk_mul_f32 v[24:25], v[42:43], v[2:3] op_sel_hi:[1,0]
	v_pk_mul_f32 v[20:21], v[26:27], v[2:3] op_sel_hi:[1,0]
	v_pk_mul_f32 v[18:19], v[24:25], v[24:25]
	v_pk_mul_f32 v[2:3], v[20:21], v[20:21]
	v_mov_b32_e32 v10, v18
	v_mov_b32_e32 v6, v19
	v_pk_add_f32 v[6:7], v[10:11], v[6:7]
	v_mov_b32_e32 v10, v3
	v_mov_b32_e32 v11, v9
	v_pk_add_f32 v[6:7], v[10:11], v[6:7]
	v_mov_b32_e32 v3, v8
	v_pk_add_f32 v[2:3], v[2:3], v[6:7]
	s_nop 1
	v_mov_b32_dpp v7, v3 quad_perm:[1,0,3,2] row_mask:0xf bank_mask:0xf
	s_nop 1
	v_mov_b32_dpp v6, v2 quad_perm:[1,0,3,2] row_mask:0xf bank_mask:0xf
	s_waitcnt lgkmcnt(0)
	v_pk_add_f32 v[2:3], v[2:3], v[6:7]
	s_nop 1
	v_mov_b32_dpp v7, v3 quad_perm:[2,3,0,1] row_mask:0xf bank_mask:0xf
	s_nop 1
	v_mov_b32_dpp v6, v2 quad_perm:[2,3,0,1] row_mask:0xf bank_mask:0xf
	s_waitcnt lgkmcnt(0)
	v_pk_add_f32 v[2:3], v[2:3], v[6:7]
	s_nop 1
	v_mov_b32_dpp v7, v3 row_half_mirror row_mask:0xf bank_mask:0xf
	s_nop 1
	v_mov_b32_dpp v6, v2 row_half_mirror row_mask:0xf bank_mask:0xf
	s_waitcnt lgkmcnt(0)
	v_pk_add_f32 v[2:3], v[2:3], v[6:7]
	s_nop 1
	v_mov_b32_dpp v7, v3 row_ror:8 row_mask:0xf bank_mask:0xf
	s_nop 1
	v_mov_b32_dpp v6, v2 row_ror:8 row_mask:0xf bank_mask:0xf
	s_waitcnt lgkmcnt(0)
; __device__ __forceinline__ unsigned cvt_pk_bf16(float lo, float hi) { unsigned r; asm volatile("v_cvt_pk_bf16_f32 %0, %1, %2" : "=v"(r) : "v"(lo), "v"(hi)); return r; }
; __device__ __forceinline__ int crow(int r, int hi) { return (r & 3) + 8 * (r >> 2) + 4 * hi; }
; __device__ __forceinline__ bool fox_block(const BlockRef& cur, BlockRef& nxt, unsigned* ctr, const unsigned* nrm, bf16_t* PROJ, bf16_t* MIX, char* lds, Seam& S, const float* __restrict__ CF, const float* __restrict__ fnorm) {
;     ...
;     for (int r = 0; r < 16; ++r) { const float rl = __builtin_amdgcn_rcpf(li_l[crow(r, hi)]); float a = 0.f;
; #pragma unroll
;         for (int d0 = 0; d0 < 4; ++d0) { const float v = o[d0][r] * rl; o[d0][r] = v; a += v * v; }
;         a += __shfl_xor(a, 1); a += __shfl_xor(a, 2); a += __shfl_xor(a, 4); a += __shfl_xor(a, 8); a += __shfl_xor(a, 16);
;         rs[r] = rsqrtf(a * (1.f / 128.f) + RMS_EPS); }
;     float gn[4];
; #pragma unroll
;     for (int d0 = 0; d0 < 4; ++d0) gn[d0] = fnorm[cur.head * 128 + d0 * 32 + r32];
;     bf16_t* Ow = cur.O + (size_t)(wid * QBLK) * DM;
; #pragma unroll
;     for (int r = 0; r < 16; ++r) { const int orow = crow(r, hi);
; #pragma unroll
;         for (int d0 = 0; d0 < 4; ++d0) { const float v = o[d0][r] * rs[r] * gn[d0];
;             const float vn = __shfl_xor(v, 1);
;             if ((r32 & 1) == 0) *(unsigned*)(Ow + (size_t)orow * DM + d0 * 32 + r32) = cvt_pk_bf16(v, vn); } }
	v_pk_add_f32 v[26:27], v[2:3], v[6:7]
	v_rcp_f32_e32 v2, v4
	v_rcp_f32_e32 v4, v5
	v_mov_b32_e32 v6, v60
	v_mov_b32_e32 v7, v44
	v_mov_b32_e32 v44, v61
	v_pk_mul_f32 v[18:19], v[6:7], v[2:3] op_sel_hi:[1,0]
	v_mov_b32_e32 v6, v12
	v_mov_b32_e32 v7, v28
	v_pk_mul_f32 v[8:9], v[44:45], v[4:5] op_sel_hi:[1,0]
	v_mov_b32_e32 v28, v13
	v_pk_mul_f32 v[22:23], v[18:19], v[18:19]
	v_pk_mul_f32 v[10:11], v[6:7], v[2:3] op_sel_hi:[1,0]
	v_pk_mul_f32 v[44:45], v[8:9], v[8:9]
	v_pk_mul_f32 v[6:7], v[28:29], v[4:5] op_sel_hi:[1,0]
	v_pk_mul_f32 v[2:3], v[10:11], v[10:11]
	v_pk_mul_f32 v[4:5], v[6:7], v[6:7]
	v_mov_b32_e32 v12, v44
	v_mov_b32_e32 v13, v22
	v_mov_b32_e32 v22, v45
	v_pk_add_f32 v[12:13], v[12:13], v[22:23]
	v_mov_b32_e32 v22, v5
	v_mov_b32_e32 v23, v3
	v_pk_add_f32 v[12:13], v[22:23], v[12:13]
	v_mov_b32_e32 v5, v2
	v_pk_add_f32 v[2:3], v[4:5], v[12:13]
	s_nop 1
	v_mov_b32_dpp v5, v3 quad_perm:[1,0,3,2] row_mask:0xf bank_mask:0xf
	s_nop 1
	v_mov_b32_dpp v4, v2 quad_perm:[1,0,3,2] row_mask:0xf bank_mask:0xf
	v_mov_b32_e32 v28, v62
	v_mov_b32_e32 v29, v46
	v_mov_b32_e32 v44, v14
	v_mov_b32_e32 v45, v30
	s_waitcnt lgkmcnt(0)
	v_pk_add_f32 v[2:3], v[2:3], v[4:5]
	s_nop 1
	v_mov_b32_dpp v5, v3 quad_perm:[2,3,0,1] row_mask:0xf bank_mask:0xf
	s_nop 1
	v_mov_b32_dpp v4, v2 quad_perm:[2,3,0,1] row_mask:0xf bank_mask:0xf
	v_mov_b32_e32 v46, v63
	v_mov_b32_e32 v30, v15
	ds_bpermute_b32 v43, v121, v27
	ds_bpermute_b32 v42, v121, v26
	s_waitcnt lgkmcnt(0)
	v_pk_add_f32 v[2:3], v[2:3], v[4:5]
	s_nop 1
	v_mov_b32_dpp v5, v3 row_half_mirror row_mask:0xf bank_mask:0xf
	s_nop 1
	v_mov_b32_dpp v4, v2 row_half_mirror row_mask:0xf bank_mask:0xf
	s_waitcnt lgkmcnt(0)
	v_pk_add_f32 v[2:3], v[2:3], v[4:5]
	s_nop 1
	v_mov_b32_dpp v5, v3 row_ror:8 row_mask:0xf bank_mask:0xf
	s_nop 1
	v_mov_b32_dpp v4, v2 row_ror:8 row_mask:0xf bank_mask:0xf
	s_waitcnt lgkmcnt(0)
	v_pk_add_f32 v[12:13], v[2:3], v[4:5]
	ds_read_b128 v[2:5], v212 offset:96
	ds_bpermute_b32 v23, v121, v13
	ds_bpermute_b32 v22, v121, v12
	s_waitcnt lgkmcnt(0)
	v_rcp_f32_e32 v2, v2
	s_nop 0
	v_pk_mul_f32 v[60:61], v[28:29], v[2:3] op_sel_hi:[1,0]
	v_pk_mul_f32 v[58:59], v[44:45], v[2:3] op_sel_hi:[1,0]
	v_rcp_f32_e32 v2, v3
	v_pk_mul_f32 v[28:29], v[60:61], v[60:61]
	v_pk_mul_f32 v[122:123], v[58:59], v[58:59]
	v_mov_b32_e32 v15, v28
	v_pk_mul_f32 v[44:45], v[46:47], v[2:3] op_sel_hi:[1,0]
	v_pk_mul_f32 v[30:31], v[30:31], v[2:3] op_sel_hi:[1,0]
	v_pk_mul_f32 v[46:47], v[44:45], v[44:45]
	v_pk_mul_f32 v[2:3], v[30:31], v[30:31]
	v_mov_b32_e32 v14, v46
	v_mov_b32_e32 v28, v47
	v_pk_add_f32 v[14:15], v[14:15], v[28:29]
	v_mov_b32_e32 v28, v3
	v_mov_b32_e32 v29, v123
	v_pk_add_f32 v[14:15], v[28:29], v[14:15]
	v_mov_b32_e32 v3, v122
	v_pk_add_f32 v[2:3], v[2:3], v[14:15]
	s_nop 1
	v_mov_b32_dpp v15, v3 quad_perm:[1,0,3,2] row_mask:0xf bank_mask:0xf
	s_nop 1
	v_mov_b32_dpp v14, v2 quad_perm:[1,0,3,2] row_mask:0xf bank_mask:0xf
	s_waitcnt lgkmcnt(0)
	v_pk_add_f32 v[2:3], v[2:3], v[14:15]
	s_nop 1
	v_mov_b32_dpp v15, v3 quad_perm:[2,3,0,1] row_mask:0xf bank_mask:0xf
	s_nop 1
	v_mov_b32_dpp v14, v2 quad_perm:[2,3,0,1] row_mask:0xf bank_mask:0xf
	s_waitcnt lgkmcnt(0)
	v_pk_add_f32 v[2:3], v[2:3], v[14:15]
	s_nop 1
	v_mov_b32_dpp v15, v3 row_half_mirror row_mask:0xf bank_mask:0xf
	s_nop 1
	v_mov_b32_dpp v14, v2 row_half_mirror row_mask:0xf bank_mask:0xf
	s_waitcnt lgkmcnt(0)
	v_pk_add_f32 v[2:3], v[2:3], v[14:15]
	s_nop 1
	v_mov_b32_dpp v15, v3 row_ror:8 row_mask:0xf bank_mask:0xf
	s_nop 1
	v_mov_b32_dpp v14, v2 row_ror:8 row_mask:0xf bank_mask:0xf
	s_waitcnt lgkmcnt(0)
	v_pk_add_f32 v[46:47], v[2:3], v[14:15]
	v_rcp_f32_e32 v2, v4
	v_mov_b32_e32 v14, v64
	v_mov_b32_e32 v15, v48
	v_mov_b32_e32 v48, v65
	v_pk_mul_f32 v[28:29], v[14:15], v[2:3] op_sel_hi:[1,0]
	v_mov_b32_e32 v14, v16
	v_mov_b32_e32 v15, v32
	v_pk_mul_f32 v[14:15], v[14:15], v[2:3] op_sel_hi:[1,0]
	v_rcp_f32_e32 v2, v5
	v_mov_b32_e32 v32, v17
	v_pk_mul_f32 v[122:123], v[28:29], v[28:29]
	v_pk_mul_f32 v[124:125], v[14:15], v[14:15]
	v_pk_mul_f32 v[4:5], v[48:49], v[2:3] op_sel_hi:[1,0]
	v_pk_mul_f32 v[2:3], v[32:33], v[2:3] op_sel_hi:[1,0]
	v_pk_mul_f32 v[48:49], v[4:5], v[4:5]
	v_pk_mul_f32 v[16:17], v[2:3], v[2:3]
	v_mov_b32_e32 v32, v48
	v_mov_b32_e32 v33, v122
	v_mov_b32_e32 v122, v49
	v_pk_add_f32 v[32:33], v[32:33], v[122:123]
	v_mov_b32_e32 v48, v17
	v_mov_b32_e32 v49, v125
	v_pk_add_f32 v[32:33], v[48:49], v[32:33]
	v_mov_b32_e32 v17, v124
	v_pk_add_f32 v[16:17], v[16:17], v[32:33]
	s_nop 1
	v_mov_b32_dpp v33, v17 quad_perm:[1,0,3,2] row_mask:0xf bank_mask:0xf
	s_nop 1
	v_mov_b32_dpp v32, v16 quad_perm:[1,0,3,2] row_mask:0xf bank_mask:0xf
	v_lshl_add_u64 v[48:49], v[196:197], 2, s[60:61]
	v_mul_f32_e32 v64, v86, v117
	ds_bpermute_b32 v63, v121, v47
	ds_bpermute_b32 v62, v121, v46
	s_waitcnt lgkmcnt(0)
	v_pk_add_f32 v[16:17], v[16:17], v[32:33]
	s_nop 1
	v_mov_b32_dpp v33, v17 quad_perm:[2,3,0,1] row_mask:0xf bank_mask:0xf
	s_nop 1
	v_mov_b32_dpp v32, v16 quad_perm:[2,3,0,1] row_mask:0xf bank_mask:0xf
	v_lshlrev_b32_e32 v196, 1, v211
	s_waitcnt lgkmcnt(0)
	v_pk_add_f32 v[16:17], v[16:17], v[32:33]
	s_nop 1
	v_mov_b32_dpp v33, v17 row_half_mirror row_mask:0xf bank_mask:0xf
	s_nop 1
	v_mov_b32_dpp v32, v16 row_half_mirror row_mask:0xf bank_mask:0xf
	s_waitcnt lgkmcnt(0)
	v_pk_add_f32 v[16:17], v[16:17], v[32:33]
	s_nop 1
	v_mov_b32_dpp v33, v17 row_ror:8 row_mask:0xf bank_mask:0xf
	s_nop 1
	v_mov_b32_dpp v32, v16 row_ror:8 row_mask:0xf bank_mask:0xf
	flat_load_dword v120, v[48:49]
	flat_load_dword v119, v[48:49] offset:128
	flat_load_dword v118, v[48:49] offset:256
	flat_load_dword v95, v[48:49] offset:384
	v_and_b32_e32 v48, 1, v202
	v_cmp_eq_u32_e64 s[10:11], 0, v48
	v_lshl_add_u64 v[48:49], s[12:13], 0, v[196:197]
	s_waitcnt lgkmcnt(0)
	v_pk_add_f32 v[16:17], v[16:17], v[32:33]
	ds_bpermute_b32 v33, v121, v17
	ds_bpermute_b32 v32, v121, v16
	v_lshlrev_b32_e32 v196, 14, v203
	v_lshl_add_u64 v[48:49], v[48:49], 0, v[196:197]
	s_waitcnt vmcnt(0)
	v_mul_f32_e32 v64, v64, v120
	s_nop 1
	v_mov_b32_dpp v65, v64 quad_perm:[1,0,3,2] row_mask:0xf bank_mask:0xf
	s_and_saveexec_b64 s[12:13], s[10:11]
	s_cbranch_execz .LBB0_2254
	s_waitcnt lgkmcnt(0)
	v_cvt_pk_bf16_f32 v64, v64, v65
	global_store_dword v[48:49], v64, off
